# row-wise phases: split-K partial-slab sums for meta rows issue all slab loads at once (same fixed add order) instead of 44 serial round trips
# speedup vs baseline: 1.0751x; 1.0115x over previous
; __device__ __forceinline__ void rowwise_phase(CP p, int mode, const float* wpost, const float* wpre, bool write_hn, int nparts) {
;     ...
;   auto loadrow = [&](int row, float4 (&t)[4], float4 (&h)[4]) {
;     if (mode == 0) {
;       const float* src = row < RREAL ? p.in[0] + (size_t)row * D : p.in[1] + (size_t)((row - RREAL) & 15) * D;
; #pragma unroll
;       for (int q = 0; q < 4; ++q) { h[q] = *reinterpret_cast<const float4*>(src + q * 256 + lane * 4); t[q] = make_float4(0.f, 0.f, 0.f, 0.f); }
;     } else {
;       const float* hr = hrow_ptr(p, row);
; #pragma unroll
;       for (int q = 0; q < 4; ++q) {
;         if (row < RREAL) {
;           {
;             const float* tp_ = tmp + (size_t)row * D + q * 256 + lane * 4;
;             t[q] = make_float4(__builtin_nontemporal_load(tp_), __builtin_nontemporal_load(tp_ + 1), __builtin_nontemporal_load(tp_ + 2), __builtin_nontemporal_load(tp_ + 3));
;           }
;         } else {
;           const float* pp = (const float*)(p.ws + WS_PART) + (size_t)(row - RREAL) * D + q * 256 + lane * 4;
;           float4 a = *reinterpret_cast<const float4*>(pp);
;           for (int kc = 1; kc < nparts; ++kc) {
;             const float4 c = *reinterpret_cast<const float4*>(pp + (size_t)kc * 128 * 1024);
;             a.x += c.x; a.y += c.y; a.z += c.z; a.w += c.w;
;           }
;           t[q] = a;
;         }
.LBB0_69:
	v_lshl_add_u64 v[118:119], v[116:117], 0, s[48:49]
	v_cmp_gt_i32_e32 vcc, s57, v118
	s_and_saveexec_b64 s[68:69], vcc
	s_cbranch_execz .LBB0_68
	v_add_u32_e32 v84, 0xffffc000, v118
	v_mov_b32_e32 v85, v149
	v_cmp_gt_i32_e64 s[40:41], s56, v118
	v_cmp_lt_i32_e64 s[38:39], s58, v118
	v_lshlrev_b64 v[88:89], 12, v[84:85]
	s_and_saveexec_b64 s[2:3], s[38:39]
	s_xor_b64 s[2:3], exec, s[2:3]
	s_cbranch_execz .LBB0_72
	v_lshl_add_u64 v[86:87], v[112:113], 0, v[88:89]
	v_subrev_u32_e32 v210, s92, v86
	v_add_u32_e32 v211, 0x0, v210
	global_load_dwordx4 v[176:179], v211, s[92:93]
	v_add_u32_e32 v211, 0x80000, v210
	global_load_dwordx4 v[180:183], v211, s[92:93]
	v_add_u32_e32 v211, 0x100000, v210
	global_load_dwordx4 v[184:187], v211, s[92:93]
	v_add_u32_e32 v211, 0x180000, v210
	global_load_dwordx4 v[188:191], v211, s[92:93]
	v_add_u32_e32 v211, 0x200000, v210
	global_load_dwordx4 v[192:195], v211, s[92:93]
	v_add_u32_e32 v211, 0x280000, v210
	global_load_dwordx4 v[196:199], v211, s[92:93]
	v_add_u32_e32 v211, 0x300000, v210
	global_load_dwordx4 v[200:203], v211, s[92:93]
	v_add_u32_e32 v211, 0x380000, v210
	global_load_dwordx4 v[204:207], v211, s[92:93]
	v_add_u32_e32 v211, 0x400000, v210
	global_load_dwordx4 v[92:95], v211, s[92:93]
	v_add_u32_e32 v211, 0x480000, v210
	global_load_dwordx4 v[96:99], v211, s[92:93]
	v_add_u32_e32 v211, 0x500000, v210
	global_load_dwordx4 v[100:103], v211, s[92:93]
	s_waitcnt vmcnt(0)
	v_pk_add_f32 v[80:81], v[176:177], v[180:181]
	v_pk_add_f32 v[82:83], v[178:179], v[182:183]
	v_pk_add_f32 v[80:81], v[80:81], v[184:185]
	v_pk_add_f32 v[82:83], v[82:83], v[186:187]
	v_pk_add_f32 v[80:81], v[80:81], v[188:189]
	v_pk_add_f32 v[82:83], v[82:83], v[190:191]
	v_pk_add_f32 v[80:81], v[80:81], v[192:193]
	v_pk_add_f32 v[82:83], v[82:83], v[194:195]
	v_pk_add_f32 v[80:81], v[80:81], v[196:197]
	v_pk_add_f32 v[82:83], v[82:83], v[198:199]
	v_pk_add_f32 v[80:81], v[80:81], v[200:201]
	v_pk_add_f32 v[82:83], v[82:83], v[202:203]
	v_pk_add_f32 v[80:81], v[80:81], v[204:205]
	v_pk_add_f32 v[82:83], v[82:83], v[206:207]
	v_pk_add_f32 v[80:81], v[80:81], v[92:93]
	v_pk_add_f32 v[82:83], v[82:83], v[94:95]
	v_pk_add_f32 v[80:81], v[80:81], v[96:97]
	v_pk_add_f32 v[82:83], v[82:83], v[98:99]
	v_pk_add_f32 v[80:81], v[80:81], v[100:101]
	v_pk_add_f32 v[82:83], v[82:83], v[102:103]

; __device__ __forceinline__ void rowwise_phase(CP p, int mode, const float* wpost, const float* wpre, bool write_hn, int nparts) {
;     ...
;       const float* hr = hrow_ptr(p, row);
; #pragma unroll
;       for (int q = 0; q < 4; ++q) {
;         if (row < RREAL) {
;           {
;             const float* tp_ = tmp + (size_t)row * D + q * 256 + lane * 4;
;             t[q] = make_float4(__builtin_nontemporal_load(tp_), __builtin_nontemporal_load(tp_ + 1), __builtin_nontemporal_load(tp_ + 2), __builtin_nontemporal_load(tp_ + 3));
;           }
;         } else {
;           const float* pp = (const float*)(p.ws + WS_PART) + (size_t)(row - RREAL) * D + q * 256 + lane * 4;
;           float4 a = *reinterpret_cast<const float4*>(pp);
;           for (int kc = 1; kc < nparts; ++kc) {
;             const float4 c = *reinterpret_cast<const float4*>(pp + (size_t)kc * 128 * 1024);
;             a.x += c.x; a.y += c.y; a.z += c.z; a.w += c.w;
;           }
;           t[q] = a;
;         }
;         h[q] = *reinterpret_cast<const float4*>(hr + q * 256 + lane * 4);
.LBB0_74:
	s_or_b64 exec, exec, s[2:3]
	v_mov_b32_e32 v86, s5
	s_waitcnt lgkmcnt(0)
	v_mov_b32_e32 v87, s31
	v_cndmask_b32_e64 v85, 0, v119, s[40:41]
	v_cndmask_b32_e64 v84, v84, v118, s[40:41]
	v_cndmask_b32_e64 v87, v86, v87, s[40:41]
	v_mov_b32_e32 v86, s4
	v_mov_b32_e32 v90, s30
	v_cndmask_b32_e64 v86, v86, v90, s[40:41]
	v_lshlrev_b64 v[84:85], 12, v[84:85]
	v_lshl_add_u64 v[84:85], v[86:87], 0, v[84:85]
	v_lshl_add_u64 v[108:109], v[84:85], 0, v[148:149]
	global_load_dwordx4 v[84:87], v[108:109], off
	v_lshl_add_u64 v[104:105], s[92:93], 0, v[88:89]
	s_and_saveexec_b64 s[2:3], s[38:39]
	s_xor_b64 s[2:3], exec, s[2:3]
	s_cbranch_execz .LBB0_76
	v_lshl_add_u64 v[106:107], v[104:105], 0, v[148:149]
	v_subrev_u32_e32 v210, s92, v106
	v_add_u32_e32 v211, 0xded0c00, v210
	global_load_dwordx4 v[176:179], v211, s[92:93]
	v_add_u32_e32 v211, 0xdf50c00, v210
	global_load_dwordx4 v[180:183], v211, s[92:93]
	v_add_u32_e32 v211, 0xdfd0c00, v210
	global_load_dwordx4 v[184:187], v211, s[92:93]
	v_add_u32_e32 v211, 0xe050c00, v210
	global_load_dwordx4 v[188:191], v211, s[92:93]
	v_add_u32_e32 v211, 0xe0d0c00, v210
	global_load_dwordx4 v[192:195], v211, s[92:93]
	v_add_u32_e32 v211, 0xe150c00, v210
	global_load_dwordx4 v[196:199], v211, s[92:93]
	v_add_u32_e32 v211, 0xe1d0c00, v210
	global_load_dwordx4 v[200:203], v211, s[92:93]
	v_add_u32_e32 v211, 0xe250c00, v210
	global_load_dwordx4 v[204:207], v211, s[92:93]
	v_add_u32_e32 v211, 0xe2d0c00, v210
	global_load_dwordx4 v[92:95], v211, s[92:93]
	v_add_u32_e32 v211, 0xe350c00, v210
	global_load_dwordx4 v[96:99], v211, s[92:93]
	v_add_u32_e32 v211, 0xe3d0c00, v210
	global_load_dwordx4 v[100:103], v211, s[92:93]
	s_waitcnt vmcnt(0)
	v_pk_add_f32 v[88:89], v[176:177], v[180:181]
	v_pk_add_f32 v[90:91], v[178:179], v[182:183]
	v_pk_add_f32 v[88:89], v[88:89], v[184:185]
	v_pk_add_f32 v[90:91], v[90:91], v[186:187]
	v_pk_add_f32 v[88:89], v[88:89], v[188:189]
	v_pk_add_f32 v[90:91], v[90:91], v[190:191]
	v_pk_add_f32 v[88:89], v[88:89], v[192:193]
	v_pk_add_f32 v[90:91], v[90:91], v[194:195]
	v_pk_add_f32 v[88:89], v[88:89], v[196:197]
	v_pk_add_f32 v[90:91], v[90:91], v[198:199]
	v_pk_add_f32 v[88:89], v[88:89], v[200:201]
	v_pk_add_f32 v[90:91], v[90:91], v[202:203]
	v_pk_add_f32 v[88:89], v[88:89], v[204:205]
	v_pk_add_f32 v[90:91], v[90:91], v[206:207]
	v_pk_add_f32 v[88:89], v[88:89], v[92:93]
	v_pk_add_f32 v[90:91], v[90:91], v[94:95]
	v_pk_add_f32 v[88:89], v[88:89], v[96:97]
	v_pk_add_f32 v[90:91], v[90:91], v[98:99]
	v_pk_add_f32 v[88:89], v[88:89], v[100:101]
	v_pk_add_f32 v[90:91], v[90:91], v[102:103]

; __device__ __forceinline__ void rowwise_phase(CP p, int mode, const float* wpost, const float* wpre, bool write_hn, int nparts) {
;     ...
;       const float* hr = hrow_ptr(p, row);
; #pragma unroll
;       for (int q = 0; q < 4; ++q) {
;         if (row < RREAL) {
;           {
;             const float* tp_ = tmp + (size_t)row * D + q * 256 + lane * 4;
;             t[q] = make_float4(__builtin_nontemporal_load(tp_), __builtin_nontemporal_load(tp_ + 1), __builtin_nontemporal_load(tp_ + 2), __builtin_nontemporal_load(tp_ + 3));
;           }
;         } else {
;           const float* pp = (const float*)(p.ws + WS_PART) + (size_t)(row - RREAL) * D + q * 256 + lane * 4;
;           float4 a = *reinterpret_cast<const float4*>(pp);
;           for (int kc = 1; kc < nparts; ++kc) {
;             const float4 c = *reinterpret_cast<const float4*>(pp + (size_t)kc * 128 * 1024);
;             a.x += c.x; a.y += c.y; a.z += c.z; a.w += c.w;
;           }
;           t[q] = a;
;         }
;         h[q] = *reinterpret_cast<const float4*>(hr + q * 256 + lane * 4);
.LBB0_78:
	s_or_b64 exec, exec, s[2:3]
	global_load_dwordx4 v[92:95], v[108:109], off offset:1024
	s_and_saveexec_b64 s[2:3], s[38:39]
	s_xor_b64 s[2:3], exec, s[2:3]
	s_cbranch_execz .LBB0_80
	v_lshl_add_u64 v[106:107], v[104:105], 0, v[148:149]
	v_subrev_u32_e32 v210, s92, v106
	v_add_u32_e32 v211, 0xded1000, v210
	global_load_dwordx4 v[176:179], v211, s[92:93]
	v_add_u32_e32 v211, 0xdf51000, v210
	global_load_dwordx4 v[180:183], v211, s[92:93]
	v_add_u32_e32 v211, 0xdfd1000, v210
	global_load_dwordx4 v[184:187], v211, s[92:93]
	v_add_u32_e32 v211, 0xe051000, v210
	global_load_dwordx4 v[188:191], v211, s[92:93]
	v_add_u32_e32 v211, 0xe0d1000, v210
	global_load_dwordx4 v[192:195], v211, s[92:93]
	v_add_u32_e32 v211, 0xe151000, v210
	global_load_dwordx4 v[196:199], v211, s[92:93]
	v_add_u32_e32 v211, 0xe1d1000, v210
	global_load_dwordx4 v[200:203], v211, s[92:93]
	v_add_u32_e32 v211, 0xe251000, v210
	global_load_dwordx4 v[204:207], v211, s[92:93]
	v_add_u32_e32 v211, 0xe2d1000, v210
	global_load_dwordx4 v[100:103], v211, s[92:93]
	v_add_u32_e32 v211, 0xe351000, v210
	global_load_dwordx4 v[128:131], v211, s[92:93]
	v_add_u32_e32 v211, 0xe3d1000, v210
	global_load_dwordx4 v[132:135], v211, s[92:93]
	s_waitcnt vmcnt(0)
	v_pk_add_f32 v[96:97], v[176:177], v[180:181]
	v_pk_add_f32 v[98:99], v[178:179], v[182:183]
	v_pk_add_f32 v[96:97], v[96:97], v[184:185]
	v_pk_add_f32 v[98:99], v[98:99], v[186:187]
	v_pk_add_f32 v[96:97], v[96:97], v[188:189]
	v_pk_add_f32 v[98:99], v[98:99], v[190:191]
	v_pk_add_f32 v[96:97], v[96:97], v[192:193]
	v_pk_add_f32 v[98:99], v[98:99], v[194:195]
	v_pk_add_f32 v[96:97], v[96:97], v[196:197]
	v_pk_add_f32 v[98:99], v[98:99], v[198:199]
	v_pk_add_f32 v[96:97], v[96:97], v[200:201]
	v_pk_add_f32 v[98:99], v[98:99], v[202:203]
	v_pk_add_f32 v[96:97], v[96:97], v[204:205]
	v_pk_add_f32 v[98:99], v[98:99], v[206:207]
	v_pk_add_f32 v[96:97], v[96:97], v[100:101]
	v_pk_add_f32 v[98:99], v[98:99], v[102:103]
	v_pk_add_f32 v[96:97], v[96:97], v[128:129]
	v_pk_add_f32 v[98:99], v[98:99], v[130:131]
	v_pk_add_f32 v[96:97], v[96:97], v[132:133]
	v_pk_add_f32 v[98:99], v[98:99], v[134:135]

; __device__ __forceinline__ void rowwise_phase(CP p, int mode, const float* wpost, const float* wpre, bool write_hn, int nparts) {
;     ...
;       const float* hr = hrow_ptr(p, row);
; #pragma unroll
;       for (int q = 0; q < 4; ++q) {
;         if (row < RREAL) {
;           {
;             const float* tp_ = tmp + (size_t)row * D + q * 256 + lane * 4;
;             t[q] = make_float4(__builtin_nontemporal_load(tp_), __builtin_nontemporal_load(tp_ + 1), __builtin_nontemporal_load(tp_ + 2), __builtin_nontemporal_load(tp_ + 3));
;           }
;         } else {
;           const float* pp = (const float*)(p.ws + WS_PART) + (size_t)(row - RREAL) * D + q * 256 + lane * 4;
;           float4 a = *reinterpret_cast<const float4*>(pp);
;           for (int kc = 1; kc < nparts; ++kc) {
;             const float4 c = *reinterpret_cast<const float4*>(pp + (size_t)kc * 128 * 1024);
;             a.x += c.x; a.y += c.y; a.z += c.z; a.w += c.w;
;           }
;           t[q] = a;
;         }
;         h[q] = *reinterpret_cast<const float4*>(hr + q * 256 + lane * 4);
.LBB0_82:
	s_or_b64 exec, exec, s[2:3]
	global_load_dwordx4 v[100:103], v[108:109], off offset:2048
	s_and_saveexec_b64 s[2:3], s[38:39]
	s_xor_b64 s[2:3], exec, s[2:3]
	s_cbranch_execz .LBB0_84
	v_lshl_add_u64 v[110:111], v[104:105], 0, v[148:149]
	v_subrev_u32_e32 v210, s92, v110
	v_add_u32_e32 v211, 0xded1400, v210
	global_load_dwordx4 v[176:179], v211, s[92:93]
	v_add_u32_e32 v211, 0xdf51400, v210
	global_load_dwordx4 v[180:183], v211, s[92:93]
	v_add_u32_e32 v211, 0xdfd1400, v210
	global_load_dwordx4 v[184:187], v211, s[92:93]
	v_add_u32_e32 v211, 0xe051400, v210
	global_load_dwordx4 v[188:191], v211, s[92:93]
	v_add_u32_e32 v211, 0xe0d1400, v210
	global_load_dwordx4 v[192:195], v211, s[92:93]
	v_add_u32_e32 v211, 0xe151400, v210
	global_load_dwordx4 v[196:199], v211, s[92:93]
	v_add_u32_e32 v211, 0xe1d1400, v210
	global_load_dwordx4 v[200:203], v211, s[92:93]
	v_add_u32_e32 v211, 0xe251400, v210
	global_load_dwordx4 v[204:207], v211, s[92:93]
	v_add_u32_e32 v211, 0xe2d1400, v210
	global_load_dwordx4 v[128:131], v211, s[92:93]
	v_add_u32_e32 v211, 0xe351400, v210
	global_load_dwordx4 v[132:135], v211, s[92:93]
	v_add_u32_e32 v211, 0xe3d1400, v210
	global_load_dwordx4 v[136:139], v211, s[92:93]
	s_waitcnt vmcnt(0)
	v_pk_add_f32 v[104:105], v[176:177], v[180:181]
	v_pk_add_f32 v[106:107], v[178:179], v[182:183]
	v_pk_add_f32 v[104:105], v[104:105], v[184:185]
	v_pk_add_f32 v[106:107], v[106:107], v[186:187]
	v_pk_add_f32 v[104:105], v[104:105], v[188:189]
	v_pk_add_f32 v[106:107], v[106:107], v[190:191]
	v_pk_add_f32 v[104:105], v[104:105], v[192:193]
	v_pk_add_f32 v[106:107], v[106:107], v[194:195]
	v_pk_add_f32 v[104:105], v[104:105], v[196:197]
	v_pk_add_f32 v[106:107], v[106:107], v[198:199]
	v_pk_add_f32 v[104:105], v[104:105], v[200:201]
	v_pk_add_f32 v[106:107], v[106:107], v[202:203]
	v_pk_add_f32 v[104:105], v[104:105], v[204:205]
	v_pk_add_f32 v[106:107], v[106:107], v[206:207]
	v_pk_add_f32 v[104:105], v[104:105], v[128:129]
	v_pk_add_f32 v[106:107], v[106:107], v[130:131]
	v_pk_add_f32 v[104:105], v[104:105], v[132:133]
	v_pk_add_f32 v[106:107], v[106:107], v[134:135]
	v_pk_add_f32 v[104:105], v[104:105], v[136:137]
	v_pk_add_f32 v[106:107], v[106:107], v[138:139]

; __device__ __forceinline__ void rowwise_phase(CP p, int mode, const float* wpost, const float* wpre, bool write_hn, int nparts) {
;     ...
;   auto loadrow = [&](int row, float4 (&t)[4], float4 (&h)[4]) {
;     if (mode == 0) {
;       const float* src = row < RREAL ? p.in[0] + (size_t)row * D : p.in[1] + (size_t)((row - RREAL) & 15) * D;
; #pragma unroll
;       for (int q = 0; q < 4; ++q) { h[q] = *reinterpret_cast<const float4*>(src + q * 256 + lane * 4); t[q] = make_float4(0.f, 0.f, 0.f, 0.f); }
;     } else {
;       const float* hr = hrow_ptr(p, row);
; #pragma unroll
;       for (int q = 0; q < 4; ++q) {
;         if (row < RREAL) {
;           {
;             const float* tp_ = tmp + (size_t)row * D + q * 256 + lane * 4;
;             t[q] = make_float4(__builtin_nontemporal_load(tp_), __builtin_nontemporal_load(tp_ + 1), __builtin_nontemporal_load(tp_ + 2), __builtin_nontemporal_load(tp_ + 3));
;           }
;         } else {
;           const float* pp = (const float*)(p.ws + WS_PART) + (size_t)(row - RREAL) * D + q * 256 + lane * 4;
;           float4 a = *reinterpret_cast<const float4*>(pp);
;           for (int kc = 1; kc < nparts; ++kc) {
;             const float4 c = *reinterpret_cast<const float4*>(pp + (size_t)kc * 128 * 1024);
;             a.x += c.x; a.y += c.y; a.z += c.z; a.w += c.w;
;           }
;           t[q] = a;
;         }
.LBB0_284:
	v_readlane_b32 s2, v253, 47
	v_readlane_b32 s3, v253, 48
	s_nop 0
	v_add_u32_e32 v136, s2, v144
	v_cmp_gt_i32_e32 vcc, s59, v136
	s_and_saveexec_b64 s[2:3], vcc
	s_cbranch_execz .LBB0_283
	v_add_u32_e32 v100, 0xffffc000, v136
	v_mov_b32_e32 v101, v149
	v_cmp_gt_i32_e64 s[40:41], s55, v136
	v_cmp_lt_i32_e64 s[38:39], s63, v136
	v_lshlrev_b64 v[104:105], 12, v[100:101]
	s_and_saveexec_b64 s[4:5], s[38:39]
	s_xor_b64 s[4:5], exec, s[4:5]
	s_cbranch_execz .LBB0_287
	v_lshl_add_u64 v[102:103], v[130:131], 0, v[104:105]
	v_subrev_u32_e32 v210, s92, v102
	v_add_u32_e32 v211, 0x0, v210
	global_load_dwordx4 v[176:179], v211, s[92:93]
	v_add_u32_e32 v211, 0x80000, v210
	global_load_dwordx4 v[180:183], v211, s[92:93]
	v_add_u32_e32 v211, 0x100000, v210
	global_load_dwordx4 v[184:187], v211, s[92:93]
	v_add_u32_e32 v211, 0x180000, v210
	global_load_dwordx4 v[188:191], v211, s[92:93]
	s_waitcnt vmcnt(0)
	v_pk_add_f32 v[96:97], v[176:177], v[180:181]
	v_pk_add_f32 v[98:99], v[178:179], v[182:183]
	v_pk_add_f32 v[96:97], v[96:97], v[184:185]
	v_pk_add_f32 v[98:99], v[98:99], v[186:187]
	v_pk_add_f32 v[96:97], v[96:97], v[188:189]
	v_pk_add_f32 v[98:99], v[98:99], v[190:191]

; __device__ __forceinline__ void rowwise_phase(CP p, int mode, const float* wpost, const float* wpre, bool write_hn, int nparts) {
;     ...
;       const float* hr = hrow_ptr(p, row);
; #pragma unroll
;       for (int q = 0; q < 4; ++q) {
;         if (row < RREAL) {
;           {
;             const float* tp_ = tmp + (size_t)row * D + q * 256 + lane * 4;
;             t[q] = make_float4(__builtin_nontemporal_load(tp_), __builtin_nontemporal_load(tp_ + 1), __builtin_nontemporal_load(tp_ + 2), __builtin_nontemporal_load(tp_ + 3));
;           }
;         } else {
;           const float* pp = (const float*)(p.ws + WS_PART) + (size_t)(row - RREAL) * D + q * 256 + lane * 4;
;           float4 a = *reinterpret_cast<const float4*>(pp);
;           for (int kc = 1; kc < nparts; ++kc) {
;             const float4 c = *reinterpret_cast<const float4*>(pp + (size_t)kc * 128 * 1024);
;             a.x += c.x; a.y += c.y; a.z += c.z; a.w += c.w;
;           }
;           t[q] = a;
;         }
;         h[q] = *reinterpret_cast<const float4*>(hr + q * 256 + lane * 4);
.LBB0_289:
	s_or_b64 exec, exec, s[4:5]
	v_mov_b32_e32 v102, s11
	s_waitcnt lgkmcnt(0)
	v_mov_b32_e32 v103, s45
	v_cndmask_b32_e64 v101, 0, v137, s[40:41]
	v_cndmask_b32_e64 v100, v100, v136, s[40:41]
	v_cndmask_b32_e64 v103, v102, v103, s[40:41]
	v_mov_b32_e32 v102, s10
	v_mov_b32_e32 v106, s44
	v_cndmask_b32_e64 v102, v102, v106, s[40:41]
	v_lshlrev_b64 v[100:101], 12, v[100:101]
	v_lshl_add_u64 v[100:101], v[102:103], 0, v[100:101]
	v_lshl_add_u64 v[124:125], v[100:101], 0, v[148:149]
	global_load_dwordx4 v[100:103], v[124:125], off
	v_lshl_add_u64 v[120:121], s[92:93], 0, v[104:105]
	s_and_saveexec_b64 s[4:5], s[38:39]
	s_xor_b64 s[4:5], exec, s[4:5]
	s_cbranch_execz .LBB0_291
	v_lshl_add_u64 v[116:117], v[120:121], 0, v[148:149]
	v_subrev_u32_e32 v210, s92, v116
	v_add_u32_e32 v211, 0xded0c00, v210
	global_load_dwordx4 v[176:179], v211, s[92:93]
	v_add_u32_e32 v211, 0xdf50c00, v210
	global_load_dwordx4 v[180:183], v211, s[92:93]
	v_add_u32_e32 v211, 0xdfd0c00, v210
	global_load_dwordx4 v[184:187], v211, s[92:93]
	v_add_u32_e32 v211, 0xe050c00, v210
	global_load_dwordx4 v[188:191], v211, s[92:93]
	s_waitcnt vmcnt(0)
	v_pk_add_f32 v[104:105], v[176:177], v[180:181]
	v_pk_add_f32 v[106:107], v[178:179], v[182:183]
	v_pk_add_f32 v[104:105], v[104:105], v[184:185]
	v_pk_add_f32 v[106:107], v[106:107], v[186:187]
	v_pk_add_f32 v[104:105], v[104:105], v[188:189]
	v_pk_add_f32 v[106:107], v[106:107], v[190:191]

; __device__ __forceinline__ void rowwise_phase(CP p, int mode, const float* wpost, const float* wpre, bool write_hn, int nparts) {
;     ...
;       const float* hr = hrow_ptr(p, row);
; #pragma unroll
;       for (int q = 0; q < 4; ++q) {
;         if (row < RREAL) {
;           {
;             const float* tp_ = tmp + (size_t)row * D + q * 256 + lane * 4;
;             t[q] = make_float4(__builtin_nontemporal_load(tp_), __builtin_nontemporal_load(tp_ + 1), __builtin_nontemporal_load(tp_ + 2), __builtin_nontemporal_load(tp_ + 3));
;           }
;         } else {
;           const float* pp = (const float*)(p.ws + WS_PART) + (size_t)(row - RREAL) * D + q * 256 + lane * 4;
;           float4 a = *reinterpret_cast<const float4*>(pp);
;           for (int kc = 1; kc < nparts; ++kc) {
;             const float4 c = *reinterpret_cast<const float4*>(pp + (size_t)kc * 128 * 1024);
;             a.x += c.x; a.y += c.y; a.z += c.z; a.w += c.w;
;           }
;           t[q] = a;
;         }
;         h[q] = *reinterpret_cast<const float4*>(hr + q * 256 + lane * 4);
.LBB0_293:
	s_or_b64 exec, exec, s[4:5]
	global_load_dwordx4 v[108:111], v[124:125], off offset:1024
	s_and_saveexec_b64 s[4:5], s[38:39]
	s_xor_b64 s[4:5], exec, s[4:5]
	s_cbranch_execz .LBB0_295
	v_lshl_add_u64 v[122:123], v[120:121], 0, v[148:149]
	v_subrev_u32_e32 v210, s92, v122
	v_add_u32_e32 v211, 0xded1000, v210
	global_load_dwordx4 v[176:179], v211, s[92:93]
	v_add_u32_e32 v211, 0xdf51000, v210
	global_load_dwordx4 v[180:183], v211, s[92:93]
	v_add_u32_e32 v211, 0xdfd1000, v210
	global_load_dwordx4 v[184:187], v211, s[92:93]
	v_add_u32_e32 v211, 0xe051000, v210
	global_load_dwordx4 v[188:191], v211, s[92:93]
	s_waitcnt vmcnt(0)
	v_pk_add_f32 v[112:113], v[176:177], v[180:181]
	v_pk_add_f32 v[114:115], v[178:179], v[182:183]
	v_pk_add_f32 v[112:113], v[112:113], v[184:185]
	v_pk_add_f32 v[114:115], v[114:115], v[186:187]
	v_pk_add_f32 v[112:113], v[112:113], v[188:189]
	v_pk_add_f32 v[114:115], v[114:115], v[190:191]

; __device__ __forceinline__ void rowwise_phase(CP p, int mode, const float* wpost, const float* wpre, bool write_hn, int nparts) {
;     ...
;       const float* hr = hrow_ptr(p, row);
; #pragma unroll
;       for (int q = 0; q < 4; ++q) {
;         if (row < RREAL) {
;           {
;             const float* tp_ = tmp + (size_t)row * D + q * 256 + lane * 4;
;             t[q] = make_float4(__builtin_nontemporal_load(tp_), __builtin_nontemporal_load(tp_ + 1), __builtin_nontemporal_load(tp_ + 2), __builtin_nontemporal_load(tp_ + 3));
;           }
;         } else {
;           const float* pp = (const float*)(p.ws + WS_PART) + (size_t)(row - RREAL) * D + q * 256 + lane * 4;
;           float4 a = *reinterpret_cast<const float4*>(pp);
;           for (int kc = 1; kc < nparts; ++kc) {
;             const float4 c = *reinterpret_cast<const float4*>(pp + (size_t)kc * 128 * 1024);
;             a.x += c.x; a.y += c.y; a.z += c.z; a.w += c.w;
;           }
;           t[q] = a;
;         }
;         h[q] = *reinterpret_cast<const float4*>(hr + q * 256 + lane * 4);
.LBB0_297:
	s_or_b64 exec, exec, s[4:5]
	global_load_dwordx4 v[116:119], v[124:125], off offset:2048
	s_and_saveexec_b64 s[4:5], s[38:39]
	s_xor_b64 s[4:5], exec, s[4:5]
	s_cbranch_execz .LBB0_299
	v_lshl_add_u64 v[126:127], v[120:121], 0, v[148:149]
	v_subrev_u32_e32 v210, s92, v126
	v_add_u32_e32 v211, 0xded1400, v210
	global_load_dwordx4 v[176:179], v211, s[92:93]
	v_add_u32_e32 v211, 0xdf51400, v210
	global_load_dwordx4 v[180:183], v211, s[92:93]
	v_add_u32_e32 v211, 0xdfd1400, v210
	global_load_dwordx4 v[184:187], v211, s[92:93]
	v_add_u32_e32 v211, 0xe051400, v210
	global_load_dwordx4 v[188:191], v211, s[92:93]
	s_waitcnt vmcnt(0)
	v_pk_add_f32 v[120:121], v[176:177], v[180:181]
	v_pk_add_f32 v[122:123], v[178:179], v[182:183]
	v_pk_add_f32 v[120:121], v[120:121], v[184:185]
	v_pk_add_f32 v[122:123], v[122:123], v[186:187]
	v_pk_add_f32 v[120:121], v[120:121], v[188:189]
	v_pk_add_f32 v[122:123], v[122:123], v[190:191]

; __device__ __forceinline__ void rowwise_phase(CP p, int mode, const float* wpost, const float* wpre, bool write_hn, int nparts) {
;     ...
;   auto loadrow = [&](int row, float4 (&t)[4], float4 (&h)[4]) {
;     if (mode == 0) {
;       const float* src = row < RREAL ? p.in[0] + (size_t)row * D : p.in[1] + (size_t)((row - RREAL) & 15) * D;
; #pragma unroll
;       for (int q = 0; q < 4; ++q) { h[q] = *reinterpret_cast<const float4*>(src + q * 256 + lane * 4); t[q] = make_float4(0.f, 0.f, 0.f, 0.f); }
;     } else {
;       const float* hr = hrow_ptr(p, row);
; #pragma unroll
;       for (int q = 0; q < 4; ++q) {
;         if (row < RREAL) {
;           {
;             const float* tp_ = tmp + (size_t)row * D + q * 256 + lane * 4;
;             t[q] = make_float4(__builtin_nontemporal_load(tp_), __builtin_nontemporal_load(tp_ + 1), __builtin_nontemporal_load(tp_ + 2), __builtin_nontemporal_load(tp_ + 3));
;           }
;         } else {
;           const float* pp = (const float*)(p.ws + WS_PART) + (size_t)(row - RREAL) * D + q * 256 + lane * 4;
;           float4 a = *reinterpret_cast<const float4*>(pp);
;           for (int kc = 1; kc < nparts; ++kc) {
;             const float4 c = *reinterpret_cast<const float4*>(pp + (size_t)kc * 128 * 1024);
;             a.x += c.x; a.y += c.y; a.z += c.z; a.w += c.w;
;           }
;           t[q] = a;
;         }
.LBB0_902:
	v_readlane_b32 s0, v253, 47
	v_readlane_b32 s1, v253, 48
	s_nop 0
	v_add_u32_e32 v136, s0, v144
	s_movk_i32 s0, 0x4080
	v_cmp_gt_i32_e32 vcc, s0, v136
	s_and_saveexec_b64 s[42:43], vcc
	s_cbranch_execz .LBB0_901
	s_movk_i32 s0, 0x4000
	v_cmp_gt_i32_e64 s[40:41], s0, v136
	s_movk_i32 s0, 0x3fff
	v_add_u32_e32 v100, 0xffffc000, v136
	v_mov_b32_e32 v101, v149
	v_cmp_lt_i32_e64 s[38:39], s0, v136
	v_lshlrev_b64 v[104:105], 12, v[100:101]
	s_and_saveexec_b64 s[2:3], s[38:39]
	s_xor_b64 s[2:3], exec, s[2:3]
	s_cbranch_execz .LBB0_905
	v_lshl_add_u64 v[102:103], v[130:131], 0, v[104:105]
	v_subrev_u32_e32 v210, s92, v102
	v_add_u32_e32 v211, 0x0, v210
	global_load_dwordx4 v[176:179], v211, s[92:93]
	v_add_u32_e32 v211, 0x80000, v210
	global_load_dwordx4 v[180:183], v211, s[92:93]
	v_add_u32_e32 v211, 0x100000, v210
	global_load_dwordx4 v[184:187], v211, s[92:93]
	v_add_u32_e32 v211, 0x180000, v210
	global_load_dwordx4 v[188:191], v211, s[92:93]
	v_add_u32_e32 v211, 0x200000, v210
	global_load_dwordx4 v[192:195], v211, s[92:93]
	v_add_u32_e32 v211, 0x280000, v210
	global_load_dwordx4 v[196:199], v211, s[92:93]
	v_add_u32_e32 v211, 0x300000, v210
	global_load_dwordx4 v[200:203], v211, s[92:93]
	v_add_u32_e32 v211, 0x380000, v210
	global_load_dwordx4 v[204:207], v211, s[92:93]
	v_add_u32_e32 v211, 0x400000, v210
	global_load_dwordx4 v[108:111], v211, s[92:93]
	v_add_u32_e32 v211, 0x480000, v210
	global_load_dwordx4 v[112:115], v211, s[92:93]
	v_add_u32_e32 v211, 0x500000, v210
	global_load_dwordx4 v[116:119], v211, s[92:93]
	s_waitcnt vmcnt(0)
	v_pk_add_f32 v[96:97], v[176:177], v[180:181]
	v_pk_add_f32 v[98:99], v[178:179], v[182:183]
	v_pk_add_f32 v[96:97], v[96:97], v[184:185]
	v_pk_add_f32 v[98:99], v[98:99], v[186:187]
	v_pk_add_f32 v[96:97], v[96:97], v[188:189]
	v_pk_add_f32 v[98:99], v[98:99], v[190:191]
	v_pk_add_f32 v[96:97], v[96:97], v[192:193]
	v_pk_add_f32 v[98:99], v[98:99], v[194:195]
	v_pk_add_f32 v[96:97], v[96:97], v[196:197]
	v_pk_add_f32 v[98:99], v[98:99], v[198:199]
	v_pk_add_f32 v[96:97], v[96:97], v[200:201]
	v_pk_add_f32 v[98:99], v[98:99], v[202:203]
	v_pk_add_f32 v[96:97], v[96:97], v[204:205]
	v_pk_add_f32 v[98:99], v[98:99], v[206:207]
	v_pk_add_f32 v[96:97], v[96:97], v[108:109]
	v_pk_add_f32 v[98:99], v[98:99], v[110:111]
	v_pk_add_f32 v[96:97], v[96:97], v[112:113]
	v_pk_add_f32 v[98:99], v[98:99], v[114:115]
	v_pk_add_f32 v[96:97], v[96:97], v[116:117]
	v_pk_add_f32 v[98:99], v[98:99], v[118:119]

; __device__ __forceinline__ void rowwise_phase(CP p, int mode, const float* wpost, const float* wpre, bool write_hn, int nparts) {
;     ...
;       const float* hr = hrow_ptr(p, row);
; #pragma unroll
;       for (int q = 0; q < 4; ++q) {
;         if (row < RREAL) {
;           {
;             const float* tp_ = tmp + (size_t)row * D + q * 256 + lane * 4;
;             t[q] = make_float4(__builtin_nontemporal_load(tp_), __builtin_nontemporal_load(tp_ + 1), __builtin_nontemporal_load(tp_ + 2), __builtin_nontemporal_load(tp_ + 3));
;           }
;         } else {
;           const float* pp = (const float*)(p.ws + WS_PART) + (size_t)(row - RREAL) * D + q * 256 + lane * 4;
;           float4 a = *reinterpret_cast<const float4*>(pp);
;           for (int kc = 1; kc < nparts; ++kc) {
;             const float4 c = *reinterpret_cast<const float4*>(pp + (size_t)kc * 128 * 1024);
;             a.x += c.x; a.y += c.y; a.z += c.z; a.w += c.w;
;           }
;           t[q] = a;
;         }
;         h[q] = *reinterpret_cast<const float4*>(hr + q * 256 + lane * 4);
.LBB0_907:
	s_or_b64 exec, exec, s[2:3]
	v_mov_b32_e32 v102, s5
	s_waitcnt lgkmcnt(0)
	v_mov_b32_e32 v103, s45
	v_cndmask_b32_e64 v101, 0, v137, s[40:41]
	v_cndmask_b32_e64 v100, v100, v136, s[40:41]
	v_cndmask_b32_e64 v103, v102, v103, s[40:41]
	v_mov_b32_e32 v102, s4
	v_mov_b32_e32 v106, s44
	v_cndmask_b32_e64 v102, v102, v106, s[40:41]
	v_lshlrev_b64 v[100:101], 12, v[100:101]
	v_lshl_add_u64 v[100:101], v[102:103], 0, v[100:101]
	v_lshl_add_u64 v[124:125], v[100:101], 0, v[148:149]
	global_load_dwordx4 v[100:103], v[124:125], off
	v_lshl_add_u64 v[120:121], s[92:93], 0, v[104:105]
	s_and_saveexec_b64 s[2:3], s[38:39]
	s_xor_b64 s[2:3], exec, s[2:3]
	s_cbranch_execz .LBB0_909
	v_lshl_add_u64 v[122:123], v[120:121], 0, v[148:149]
	v_subrev_u32_e32 v210, s92, v122
	v_add_u32_e32 v211, 0xded0c00, v210
	global_load_dwordx4 v[176:179], v211, s[92:93]
	v_add_u32_e32 v211, 0xdf50c00, v210
	global_load_dwordx4 v[180:183], v211, s[92:93]
	v_add_u32_e32 v211, 0xdfd0c00, v210
	global_load_dwordx4 v[184:187], v211, s[92:93]
	v_add_u32_e32 v211, 0xe050c00, v210
	global_load_dwordx4 v[188:191], v211, s[92:93]
	v_add_u32_e32 v211, 0xe0d0c00, v210
	global_load_dwordx4 v[192:195], v211, s[92:93]
	v_add_u32_e32 v211, 0xe150c00, v210
	global_load_dwordx4 v[196:199], v211, s[92:93]
	v_add_u32_e32 v211, 0xe1d0c00, v210
	global_load_dwordx4 v[200:203], v211, s[92:93]
	v_add_u32_e32 v211, 0xe250c00, v210
	global_load_dwordx4 v[204:207], v211, s[92:93]
	v_add_u32_e32 v211, 0xe2d0c00, v210
	global_load_dwordx4 v[108:111], v211, s[92:93]
	v_add_u32_e32 v211, 0xe350c00, v210
	global_load_dwordx4 v[112:115], v211, s[92:93]
	v_add_u32_e32 v211, 0xe3d0c00, v210
	global_load_dwordx4 v[116:119], v211, s[92:93]
	s_waitcnt vmcnt(0)
	v_pk_add_f32 v[104:105], v[176:177], v[180:181]
	v_pk_add_f32 v[106:107], v[178:179], v[182:183]
	v_pk_add_f32 v[104:105], v[104:105], v[184:185]
	v_pk_add_f32 v[106:107], v[106:107], v[186:187]
	v_pk_add_f32 v[104:105], v[104:105], v[188:189]
	v_pk_add_f32 v[106:107], v[106:107], v[190:191]
	v_pk_add_f32 v[104:105], v[104:105], v[192:193]
	v_pk_add_f32 v[106:107], v[106:107], v[194:195]
	v_pk_add_f32 v[104:105], v[104:105], v[196:197]
	v_pk_add_f32 v[106:107], v[106:107], v[198:199]
	v_pk_add_f32 v[104:105], v[104:105], v[200:201]
	v_pk_add_f32 v[106:107], v[106:107], v[202:203]
	v_pk_add_f32 v[104:105], v[104:105], v[204:205]
	v_pk_add_f32 v[106:107], v[106:107], v[206:207]
	v_pk_add_f32 v[104:105], v[104:105], v[108:109]
	v_pk_add_f32 v[106:107], v[106:107], v[110:111]
	v_pk_add_f32 v[104:105], v[104:105], v[112:113]
	v_pk_add_f32 v[106:107], v[106:107], v[114:115]
	v_pk_add_f32 v[104:105], v[104:105], v[116:117]
	v_pk_add_f32 v[106:107], v[106:107], v[118:119]

; __device__ __forceinline__ void rowwise_phase(CP p, int mode, const float* wpost, const float* wpre, bool write_hn, int nparts) {
;     ...
;       const float* hr = hrow_ptr(p, row);
; #pragma unroll
;       for (int q = 0; q < 4; ++q) {
;         if (row < RREAL) {
;           {
;             const float* tp_ = tmp + (size_t)row * D + q * 256 + lane * 4;
;             t[q] = make_float4(__builtin_nontemporal_load(tp_), __builtin_nontemporal_load(tp_ + 1), __builtin_nontemporal_load(tp_ + 2), __builtin_nontemporal_load(tp_ + 3));
;           }
;         } else {
;           const float* pp = (const float*)(p.ws + WS_PART) + (size_t)(row - RREAL) * D + q * 256 + lane * 4;
;           float4 a = *reinterpret_cast<const float4*>(pp);
;           for (int kc = 1; kc < nparts; ++kc) {
;             const float4 c = *reinterpret_cast<const float4*>(pp + (size_t)kc * 128 * 1024);
;             a.x += c.x; a.y += c.y; a.z += c.z; a.w += c.w;
;           }
;           t[q] = a;
;         }
;         h[q] = *reinterpret_cast<const float4*>(hr + q * 256 + lane * 4);
.LBB0_911:
	s_or_b64 exec, exec, s[2:3]
	global_load_dwordx4 v[108:111], v[124:125], off offset:1024
	s_and_saveexec_b64 s[2:3], s[38:39]
	s_xor_b64 s[2:3], exec, s[2:3]
	s_cbranch_execz .LBB0_913
	v_lshl_add_u64 v[122:123], v[120:121], 0, v[148:149]
	v_subrev_u32_e32 v210, s92, v122
	v_add_u32_e32 v211, 0xded1000, v210
	global_load_dwordx4 v[176:179], v211, s[92:93]
	v_add_u32_e32 v211, 0xdf51000, v210
	global_load_dwordx4 v[180:183], v211, s[92:93]
	v_add_u32_e32 v211, 0xdfd1000, v210
	global_load_dwordx4 v[184:187], v211, s[92:93]
	v_add_u32_e32 v211, 0xe051000, v210
	global_load_dwordx4 v[188:191], v211, s[92:93]
	v_add_u32_e32 v211, 0xe0d1000, v210
	global_load_dwordx4 v[192:195], v211, s[92:93]
	v_add_u32_e32 v211, 0xe151000, v210
	global_load_dwordx4 v[196:199], v211, s[92:93]
	v_add_u32_e32 v211, 0xe1d1000, v210
	global_load_dwordx4 v[200:203], v211, s[92:93]
	v_add_u32_e32 v211, 0xe251000, v210
	global_load_dwordx4 v[204:207], v211, s[92:93]
	v_add_u32_e32 v211, 0xe2d1000, v210
	global_load_dwordx4 v[116:119], v211, s[92:93]
	v_add_u32_e32 v211, 0xe351000, v210
	global_load_dwordx4 v[152:155], v211, s[92:93]
	v_add_u32_e32 v211, 0xe3d1000, v210
	global_load_dwordx4 v[156:159], v211, s[92:93]
	s_waitcnt vmcnt(0)
	v_pk_add_f32 v[112:113], v[176:177], v[180:181]
	v_pk_add_f32 v[114:115], v[178:179], v[182:183]
	v_pk_add_f32 v[112:113], v[112:113], v[184:185]
	v_pk_add_f32 v[114:115], v[114:115], v[186:187]
	v_pk_add_f32 v[112:113], v[112:113], v[188:189]
	v_pk_add_f32 v[114:115], v[114:115], v[190:191]
	v_pk_add_f32 v[112:113], v[112:113], v[192:193]
	v_pk_add_f32 v[114:115], v[114:115], v[194:195]
	v_pk_add_f32 v[112:113], v[112:113], v[196:197]
	v_pk_add_f32 v[114:115], v[114:115], v[198:199]
	v_pk_add_f32 v[112:113], v[112:113], v[200:201]
	v_pk_add_f32 v[114:115], v[114:115], v[202:203]
	v_pk_add_f32 v[112:113], v[112:113], v[204:205]
	v_pk_add_f32 v[114:115], v[114:115], v[206:207]
	v_pk_add_f32 v[112:113], v[112:113], v[116:117]
	v_pk_add_f32 v[114:115], v[114:115], v[118:119]
	v_pk_add_f32 v[112:113], v[112:113], v[152:153]
	v_pk_add_f32 v[114:115], v[114:115], v[154:155]
	v_pk_add_f32 v[112:113], v[112:113], v[156:157]
	v_pk_add_f32 v[114:115], v[114:115], v[158:159]

; __device__ __forceinline__ void rowwise_phase(CP p, int mode, const float* wpost, const float* wpre, bool write_hn, int nparts) {
;     ...
;       const float* hr = hrow_ptr(p, row);
; #pragma unroll
;       for (int q = 0; q < 4; ++q) {
;         if (row < RREAL) {
;           {
;             const float* tp_ = tmp + (size_t)row * D + q * 256 + lane * 4;
;             t[q] = make_float4(__builtin_nontemporal_load(tp_), __builtin_nontemporal_load(tp_ + 1), __builtin_nontemporal_load(tp_ + 2), __builtin_nontemporal_load(tp_ + 3));
;           }
;         } else {
;           const float* pp = (const float*)(p.ws + WS_PART) + (size_t)(row - RREAL) * D + q * 256 + lane * 4;
;           float4 a = *reinterpret_cast<const float4*>(pp);
;           for (int kc = 1; kc < nparts; ++kc) {
;             const float4 c = *reinterpret_cast<const float4*>(pp + (size_t)kc * 128 * 1024);
;             a.x += c.x; a.y += c.y; a.z += c.z; a.w += c.w;
;           }
;           t[q] = a;
;         }
;         h[q] = *reinterpret_cast<const float4*>(hr + q * 256 + lane * 4);
.LBB0_915:
	s_or_b64 exec, exec, s[2:3]
	global_load_dwordx4 v[116:119], v[124:125], off offset:2048
	s_and_saveexec_b64 s[2:3], s[38:39]
	s_xor_b64 s[2:3], exec, s[2:3]
	s_cbranch_execz .LBB0_917
	v_lshl_add_u64 v[126:127], v[120:121], 0, v[148:149]
	v_subrev_u32_e32 v210, s92, v126
	v_add_u32_e32 v211, 0xded1400, v210
	global_load_dwordx4 v[176:179], v211, s[92:93]
	v_add_u32_e32 v211, 0xdf51400, v210
	global_load_dwordx4 v[180:183], v211, s[92:93]
	v_add_u32_e32 v211, 0xdfd1400, v210
	global_load_dwordx4 v[184:187], v211, s[92:93]
	v_add_u32_e32 v211, 0xe051400, v210
	global_load_dwordx4 v[188:191], v211, s[92:93]
	v_add_u32_e32 v211, 0xe0d1400, v210
	global_load_dwordx4 v[192:195], v211, s[92:93]
	v_add_u32_e32 v211, 0xe151400, v210
	global_load_dwordx4 v[196:199], v211, s[92:93]
	v_add_u32_e32 v211, 0xe1d1400, v210
	global_load_dwordx4 v[200:203], v211, s[92:93]
	v_add_u32_e32 v211, 0xe251400, v210
	global_load_dwordx4 v[204:207], v211, s[92:93]
	v_add_u32_e32 v211, 0xe2d1400, v210
	global_load_dwordx4 v[152:155], v211, s[92:93]
	v_add_u32_e32 v211, 0xe351400, v210
	global_load_dwordx4 v[156:159], v211, s[92:93]
	v_add_u32_e32 v211, 0xe3d1400, v210
	global_load_dwordx4 v[160:163], v211, s[92:93]
	s_waitcnt vmcnt(0)
	v_pk_add_f32 v[120:121], v[176:177], v[180:181]
	v_pk_add_f32 v[122:123], v[178:179], v[182:183]
	v_pk_add_f32 v[120:121], v[120:121], v[184:185]
	v_pk_add_f32 v[122:123], v[122:123], v[186:187]
	v_pk_add_f32 v[120:121], v[120:121], v[188:189]
	v_pk_add_f32 v[122:123], v[122:123], v[190:191]
	v_pk_add_f32 v[120:121], v[120:121], v[192:193]
	v_pk_add_f32 v[122:123], v[122:123], v[194:195]
	v_pk_add_f32 v[120:121], v[120:121], v[196:197]
	v_pk_add_f32 v[122:123], v[122:123], v[198:199]
	v_pk_add_f32 v[120:121], v[120:121], v[200:201]
	v_pk_add_f32 v[122:123], v[122:123], v[202:203]
	v_pk_add_f32 v[120:121], v[120:121], v[204:205]
	v_pk_add_f32 v[122:123], v[122:123], v[206:207]
	v_pk_add_f32 v[120:121], v[120:121], v[152:153]
	v_pk_add_f32 v[122:123], v[122:123], v[154:155]
	v_pk_add_f32 v[120:121], v[120:121], v[156:157]
	v_pk_add_f32 v[122:123], v[122:123], v[158:159]
	v_pk_add_f32 v[120:121], v[120:121], v[160:161]
	v_pk_add_f32 v[122:123], v[122:123], v[162:163]
